# k=3: tile-owner index rotated by 64/128 for the 2nd/3rd LoRA GEMM so partial last rounds land on different workgroups
# speedup vs baseline: 1.0020x; 1.0020x over previous
;     __host__ __device__ bool next(int i, Unit& u) const {
;         const long L = (long)i * G + c; if (L >= nwg) return false;
;         int wgid = (int)L; { const int q = nwg / NXCD, r = nwg % NXCD, xcd = wgid % NXCD, off = wgid / NXCD; wgid = (xcd < r ? xcd * (q + 1) : r * (q + 1) + (xcd - r) * q) + off; }
;         const int nig = WGM * nN, gid = wgid / nig, fm = gid * WGM, gsz = (nM - fm) < WGM ? (nM - fm) : WGM;
;         u.pm = fm + ((wgid % nig) % gsz); u.pn = (wgid % nig) / gsz; return true;
; template <class Epi, class Sched, bool ALIGN_EPI = false, bool SP2 = false>
; __device__ __forceinline__ void gemm_phase(PG8_LAS unsigned char* lds, const Gemm g, const Sched& S, const Epi& E, const int tid_in) {
;     const int tid = tid_in, wid = __builtin_amdgcn_readfirstlane(tid >> 6), lane = tid & 63, wr = wid >> 2, wc = wid & 3, fr = lane & 15, fq = lane >> 4;
;     const int K = g.K, nt = K / BK;
;     unsigned voffA[2], voffB[2];
; #pragma unroll
;     for (int i = 0; i < 2; ++i) { int R, C; stage_rc(tid * 16 + i * 8192, R, C); const int Rb = Epi::PERM ? ((R & ~31) + perm32(R & 31)) : R;
;         voffA[i] = (unsigned)(R * K + C) * 2u; voffB[i] = (unsigned)(Rb * K + C) * 2u; }
;     const size_t kstep = (size_t)(BK * 2);
;     const size_t hstep = (size_t)HALF * K * 2;
;     const size_t tstep = 2 * hstep;
;     const unsigned ldsw = (unsigned)wid * 1024u;
;     const int aoff = lds_byte(wr * 64 + fr, fq * 8), boff = lds_byte(wc * 32 + fr, fq * 8);
.LBB0_388:
	s_movk_i32 s6, 0x80
	s_andn2_b64 vcc, exec, s[4:5]
	v_readfirstlane_b32 s33, v178
	s_cbranch_vccnz .LBB0_410
	v_lshlrev_b32_e32 v0, 4, v178
	v_add_u32_e32 v2, 0x2000, v0
	v_ashrrev_i32_e32 v3, 31, v2
	v_lshrrev_b32_e32 v3, 22, v3
	v_add_u32_e32 v3, v2, v3
	v_ashrrev_i32_e32 v3, 10, v3
	v_mul_i32_i24_e32 v4, 0x400, v3
	v_sub_u32_e32 v2, v2, v4
	s_load_dwordx2 s[4:5], s[74:75], 0x110
	v_lshrrev_b32_e32 v4, 4, v2
	v_bitop3_b32 v2, v4, v2, 32 bitop3:0x6c
	v_ashrrev_i32_e32 v4, 31, v2
	v_lshrrev_b32_e32 v4, 26, v4
	v_add_u32_e32 v4, v2, v4
	v_lshlrev_b32_e32 v6, 3, v3
	s_waitcnt lgkmcnt(0)
	s_add_u32 s1, s4, 0x20080000
	v_ashrrev_i32_e32 v5, 6, v4
	v_and_b32_e32 v6, -16, v6
	v_lshlrev_b32_e32 v3, 5, v3
	s_addc_u32 s3, s5, 0
	v_add_u32_e32 v6, v5, v6
	v_and_b32_e32 v14, 32, v3
	v_and_b32_e32 v3, 0xc0, v4
	s_add_u32 s10, s4, 0x3100000
	v_and_b32_e32 v5, 3, v5
	s_mov_b32 s4, 0x7fffffe0
	v_lshrrev_b32_e32 v7, 2, v6
	v_lshlrev_b32_e32 v8, 1, v6
	v_sub_u32_e32 v2, v2, v3
	v_and_or_b32 v5, v6, s4, v5
	v_and_b32_e32 v7, 4, v7
	v_and_b32_e32 v8, 24, v8
	v_ashrrev_i16_sdwa v2, v189, sext(v2) dst_sel:DWORD dst_unused:UNUSED_PAD src0_sel:DWORD src1_sel:BYTE_0
	v_or3_b32 v5, v5, v7, v8
	v_bfe_i32 v15, v2, 0, 16
	v_mul_lo_u32 v5, s6, v5
	v_add_u32_e32 v2, v14, v15
	v_mul_lo_u32 v16, s6, v6
	v_add_lshl_u32 v134, v5, v2, 1
	v_add_lshl_u32 v136, v16, v2, 1
	v_bfe_i32 v2, v178, 27, 1
	v_lshrrev_b32_e32 v2, 22, v2
	v_add_u32_e32 v2, v0, v2
	v_and_b32_e32 v2, 0xfffffc00, v2
	v_sub_u32_e32 v0, v0, v2
	v_lshrrev_b32_e32 v2, 4, v0
	v_ashrrev_i32_e32 v4, 31, v178
	v_bitop3_b32 v2, v2, v0, 32 bitop3:0x6c
	v_lshrrev_b32_e32 v4, 26, v4
	v_ashrrev_i32_e32 v0, 31, v2
	v_add_u32_e32 v4, v178, v4
	v_lshrrev_b32_e32 v0, 26, v0
	v_ashrrev_i32_e32 v4, 6, v4
	v_add_u32_e32 v3, v2, v0
	v_lshlrev_b32_e32 v5, 3, v4
	v_ashrrev_i32_e32 v0, 6, v3
	v_and_b32_e32 v5, -16, v5
	s_addc_u32 s11, s5, 0
	v_add_u32_e32 v5, v0, v5
	v_and_b32_e32 v0, 3, v0
	s_cmp_lg_u32 s0, 0x100
	s_cbranch_scc1 .Lk3_noshift_b
	s_add_i32 s2, s2, 64
	s_and_b32 s2, s2, 0xff
.Lk3_noshift_b:
	s_ashr_i32 s16, s2, 31
	v_and_or_b32 v0, v5, s4, v0
	s_lshr_b32 s4, s16, 29
	s_add_i32 s4, s2, s4
	s_ashr_i32 s36, s33, 6
	s_ashr_i32 s7, s6, 31
	s_ashr_i32 s5, s4, 3
	s_and_b32 s4, s4, -8
	s_ashr_i32 s42, s33, 8
	s_lshl_b64 s[46:47], s[6:7], 8
	s_lshl_b64 s[48:49], s[6:7], 9
	s_lshl_b32 s14, s36, 10
	s_sub_i32 s4, s2, s4
	s_mov_b32 s87, s67
	s_cmp_lt_i32 s4, 0
	s_movk_i32 s67, 0x49
	s_cselect_b32 s17, s67, 0x48
	s_mul_i32 s4, s17, s4
	s_add_i32 s4, s4, s5
	s_ashr_i32 s5, s4, 31
	s_lshr_b32 s5, s5, 26
	s_add_i32 s5, s4, s5
	s_ashr_i32 s17, s5, 6
	s_and_b32 s5, s5, 0xffc0
	s_sub_i32 s4, s4, s5
	s_bfe_i32 s5, s4, 0x80000
	s_bfe_u32 s5, s5, 0x3000c
	s_add_i32 s5, s4, s5
	s_bfe_i32 s18, s5, 0x80000
	s_and_b32 s5, s5, 0xf8
	s_sub_i32 s4, s4, s5
	s_lshl_b32 s17, s17, 3
	s_sext_i32_i8 s4, s4
	s_add_i32 s27, s17, s4
	s_ashr_i32 s4, s27, 31
	s_mul_i32 s4, s48, s4
	s_mul_hi_u32 s5, s48, s27
	s_sext_i32_i16 s37, s18
	s_add_i32 s17, s5, s4
	s_lshr_b64 s[4:5], s[6:7], 23
	s_lshr_b32 s18, s37, 3
	s_mul_i32 s5, s4, s27
	v_lshrrev_b32_e32 v6, 2, v5
	v_lshlrev_b32_e32 v7, 1, v5
	s_add_i32 s39, s17, s5
	s_bfe_i64 s[34:35], s[18:19], 0x100000
	s_ashr_i32 s5, s37, 3
	v_and_b32_e32 v6, 4, v6
	v_and_b32_e32 v7, 24, v7
	v_and_b32_e32 v3, 0xc0, v3
	s_mul_hi_u32 s17, s48, s5
	s_mul_i32 s34, s48, s35
	v_or3_b32 v0, v0, v6, v7
	v_sub_u32_e32 v2, v2, v3
	s_add_i32 s17, s17, s34
	s_mul_i32 s4, s4, s5
	v_mul_lo_u32 v6, s6, v0
	v_lshlrev_b32_e32 v0, 5, v4
	v_ashrrev_i16_sdwa v2, v189, sext(v2) dst_sel:DWORD dst_unused:UNUSED_PAD src0_sel:DWORD src1_sel:BYTE_0
	s_add_i32 s17, s17, s4
	s_mul_i32 s4, s48, s5
	v_and_b32_e32 v0, 32, v0
	v_bfe_i32 v17, v2, 0, 16
	s_add_u32 s4, s10, s4
	v_add_u32_e32 v2, v0, v17
	s_addc_u32 s5, s11, s17
	s_add_i32 s17, s14, 0
	v_add_lshl_u32 v138, v6, v2, 1
	s_add_i32 m0, s17, 0x10000
	s_mul_i32 s40, s48, s27
	global_load_lds_dwordx4 v138, s[4:5]
	s_add_i32 m0, s17, 0x12000
	s_add_u32 s50, s4, s46
	global_load_lds_dwordx4 v134, s[4:5]
	s_addc_u32 s51, s5, s47
	s_add_i32 m0, s17, 0x14000
	v_mul_lo_u32 v18, s6, v5
	global_load_lds_dwordx4 v138, s[50:51]
	s_add_i32 m0, s17, 0x16000
	s_add_u32 s58, s1, s40
	s_addc_u32 s59, s3, s39
	s_add_i32 s34, s17, 0x2000
	v_add_lshl_u32 v140, v18, v2, 1
	global_load_lds_dwordx4 v134, s[50:51]
	s_mov_b32 m0, s17
	s_add_u32 s40, s58, s46
	global_load_lds_dwordx4 v140, s[58:59]
	s_mov_b32 m0, s34
	s_addc_u32 s41, s59, s47
	s_add_i32 s35, s17, 0x4000
	global_load_lds_dwordx4 v136, s[58:59]
	s_mov_b32 m0, s35
	s_add_i32 s37, s17, 0x6000
	global_load_lds_dwordx4 v140, s[40:41]
	s_mov_b32 m0, s37
	v_mov_b32_e32 v139, v1
	global_load_lds_dwordx4 v136, s[40:41]
	s_load_dwordx2 s[40:41], s[74:75], 0x98
	v_mov_b32_e32 v135, v1
	v_mov_b32_e32 v141, v1
	v_mov_b32_e32 v137, v1
	s_cmp_eq_u32 s42, 1
	v_lshl_add_u64 v[10:11], s[4:5], 0, v[138:139]
	v_lshl_add_u64 v[6:7], s[4:5], 0, v[134:135]
	v_lshl_add_u64 v[4:5], s[50:51], 0, v[138:139]
	v_lshl_add_u64 v[2:3], s[50:51], 0, v[134:135]
	v_lshl_add_u64 v[8:9], s[58:59], 0, v[140:141]
	s_cselect_b64 s[50:51], -1, 0
	s_cmp_lg_u32 s42, 1
	v_lshl_add_u64 v[12:13], s[58:59], 0, v[136:137]
	s_cbranch_scc1 .LBB0_391
	s_barrier

; __global__ void __launch_bounds__(512, 2) mega_fwd(Args a_) {
;     ...
;                 OpAA o2{(bf16_t*)(ws + WS_AA0), (bf16_t*)(ws + WS_AA1), a.in[19] + l * 2048};
;                 run_gemm(ti, lds, (const bf16_t*)(ws + WS_LIA), (const bf16_t*)(ws + WS_LAT), M, 2048, 128, o2);
;                 OpG o3{(bf16_t*)(ws + WS_G)};
;                 run_gemm(ti, lds, (const bf16_t*)(ws + WS_LIG), (const bf16_t*)(ws + WS_LGT), M, 1024, 256, o3);
.LBB0_410:
	s_cmp_lg_u32 s0, 0x100
	s_cbranch_scc1 .Lk3_noshift_c
	s_add_i32 s2, s2, 64
	s_and_b32 s2, s2, 0xff
